# branch-merge and k_rope passes: loads hoisted so each iteration has one memory round trip; banded-attention sink wait deferred
# speedup vs baseline: 1.0010x; 1.0010x over previous
.LBB0_347:
	v_ashrrev_i32_e32 v8, 4, v6
	v_mad_i64_i32 v[10:11], s[0:1], v8, s75, v[4:5]
	global_load_ushort v7, v[10:11], off offset:1280
	v_ashrrev_i32_e32 v9, 31, v8
	global_load_ushort v10, v[10:11], off offset:1312
	v_add_u32_e32 v6, s8, v6
	s_mov_b32 s0, 0x7ffff
	v_lshlrev_b64 v[8:9], 6, v[8:9]
	v_cmp_lt_i32_e32 vcc, s0, v6
	v_lshl_add_u64 v[8:9], v[2:3], 0, v[8:9]
	s_or_b64 s[36:37], vcc, s[36:37]
	v_and_b32_e32 v14, 0x7fffe, v0
	v_lshlrev_b32_e32 v14, 2, v14
	global_load_dwordx2 v[14:15], v14, s[4:5]
	v_add_u32_e32 v0, s34, v0
	s_waitcnt vmcnt(0)
	v_lshlrev_b32_e32 v7, 16, v7
	v_lshlrev_b32_e32 v12, 16, v10
	v_mul_f32_e32 v13, v15, v12
	v_fma_f32 v13, v14, v7, -v13
	v_mul_f32_e32 v10, v14, v12
	v_cvt_pk_bf16_f32 v13, v13, v1
	global_store_short v[8:9], v13, off
	v_fmac_f32_e32 v10, v15, v7
	v_cvt_pk_bf16_f32 v7, v10, v1
	global_store_short v[8:9], v7, off offset:32
	s_andn2_b64 exec, exec, s[36:37]
	s_cbranch_execnz .LBB0_347

.LBB0_355:
	v_ashrrev_i32_e32 v6, 5, v8
	v_bfe_u32 v10, v8, 3, 2
	v_ashrrev_i32_e32 v7, 31, v6
	v_and_b32_e32 v22, 56, v9
	v_lshl_add_u64 v[2:3], v[6:7], 4, s[68:69]
	v_lshlrev_b32_e32 v0, 2, v10
	v_lshl_add_u64 v[2:3], v[2:3], 0, v[0:1]
	v_add_co_u32_e32 v4, vcc, 0x80000, v2
	s_nop 1
	v_addc_co_u32_e32 v5, vcc, 0, v3, vcc
	v_add_co_u32_e32 v28, vcc, 0x100000, v2
	s_nop 1
	v_addc_co_u32_e32 v29, vcc, 0, v3, vcc
	v_lshlrev_b64 v[12:13], 8, v[6:7]
	v_lshlrev_b32_e32 v14, 6, v10
	v_or3_b32 v12, v12, v14, v22
	v_lshlrev_b64 v[16:17], 1, v[12:13]
	v_lshl_add_u64 v[32:33], s[66:67], 0, v[16:17]
	v_lshl_add_u64 v[34:35], s[70:71], 0, v[16:17]
	v_lshl_add_u64 v[36:37], s[72:73], 0, v[16:17]
	global_load_dword v30, v[2:3], off
	global_load_dword v31, v[4:5], off
	global_load_dword v38, v[28:29], off
	global_load_dwordx4 v[40:43], v[32:33], off
	global_load_dwordx4 v[44:47], v[34:35], off
	global_load_dwordx4 v[48:51], v[36:37], off
	v_add_u32_e32 v8, s4, v8
	v_add_u32_e32 v9, s74, v9
	v_mov_b64_e32 v[12:13], s[26:27]
	v_mad_i64_i32 v[6:7], s[0:1], v6, s75, v[12:13]
	v_lshlrev_b32_e32 v0, 7, v10
	v_lshl_add_u64 v[6:7], v[6:7], 0, v[0:1]
	v_lshlrev_b32_e32 v0, 1, v22
	v_lshl_add_u64 v[6:7], v[6:7], 0, v[0:1]
	v_add_co_u32_e32 v6, vcc, 0x10000000, v6
	s_nop 1
	v_addc_co_u32_e32 v7, vcc, 0, v7, vcc
	s_mov_b32 s0, 0xfffff
	v_cmp_lt_i32_e32 vcc, s0, v8
	s_or_b64 s[38:39], vcc, s[38:39]
	s_waitcnt vmcnt(3)
	v_max3_f32 v3, v30, v31, v38
	v_sub_f32_e32 v0, v30, v3
	v_mul_f32_e32 v0, 0x3fb8aa3b, v0
	v_exp_f32_e32 v21, v0
	v_sub_f32_e32 v0, v31, v3
	v_mul_f32_e32 v0, 0x3fb8aa3b, v0
	v_exp_f32_e32 v4, v0
	v_sub_f32_e32 v0, v38, v3
	v_mul_f32_e32 v0, 0x3fb8aa3b, v0
	v_exp_f32_e32 v20, v0
	v_add_f32_e32 v0, v21, v4
	v_add_f32_e32 v0, v20, v0
	v_div_scale_f32 v2, s[0:1], v0, v0, 1.0
	v_rcp_f32_e32 v3, v2
	s_nop 0
	v_fma_f32 v5, -v2, v3, 1.0
	v_fmac_f32_e32 v3, v5, v3
	v_div_scale_f32 v5, vcc, 1.0, v0, 1.0
	v_mul_f32_e32 v11, v5, v3
	v_fma_f32 v12, -v2, v11, v5
	v_fmac_f32_e32 v11, v12, v3
	v_fma_f32 v2, -v2, v11, v5
	v_div_fmas_f32 v2, v2, v3, v11
	v_div_fixup_f32 v0, v2, v0, 1.0
	v_mul_f32_e32 v11, v4, v0
	v_mul_f32_e32 v13, v21, v0
	v_mul_f32_e32 v12, v20, v0
	s_waitcnt vmcnt(0)
	v_lshlrev_b32_e32 v52, 16, v40
	v_lshlrev_b32_e32 v53, 16, v44
	v_lshlrev_b32_e32 v54, 16, v48
	v_mul_f32_e32 v55, v13, v52
	v_mul_f32_e32 v54, v12, v54
	v_fmac_f32_e32 v55, v11, v53
	v_add_f32_e32 v55, v54, v55
	v_and_b32_e32 v56, 0xffff0000, v40
	v_and_b32_e32 v57, 0xffff0000, v44
	v_and_b32_e32 v58, 0xffff0000, v48
	v_mul_f32_e32 v59, v13, v56
	v_mul_f32_e32 v58, v12, v58
	v_fmac_f32_e32 v59, v11, v57
	v_add_f32_e32 v59, v58, v59
	v_cvt_pk_bf16_f32 v60, v55, v59
	v_lshlrev_b32_e32 v52, 16, v41
	v_lshlrev_b32_e32 v53, 16, v45
	v_lshlrev_b32_e32 v54, 16, v49
	v_mul_f32_e32 v55, v13, v52
	v_mul_f32_e32 v54, v12, v54
	v_fmac_f32_e32 v55, v11, v53
	v_add_f32_e32 v55, v54, v55
	v_and_b32_e32 v56, 0xffff0000, v41
	v_and_b32_e32 v57, 0xffff0000, v45
	v_and_b32_e32 v58, 0xffff0000, v49
	v_mul_f32_e32 v59, v13, v56
	v_mul_f32_e32 v58, v12, v58
	v_fmac_f32_e32 v59, v11, v57
	v_add_f32_e32 v59, v58, v59
	v_cvt_pk_bf16_f32 v61, v55, v59
	v_lshlrev_b32_e32 v52, 16, v42
	v_lshlrev_b32_e32 v53, 16, v46
	v_lshlrev_b32_e32 v54, 16, v50
	v_mul_f32_e32 v55, v13, v52
	v_mul_f32_e32 v54, v12, v54
	v_fmac_f32_e32 v55, v11, v53
	v_add_f32_e32 v55, v54, v55
	v_and_b32_e32 v56, 0xffff0000, v42
	v_and_b32_e32 v57, 0xffff0000, v46
	v_and_b32_e32 v58, 0xffff0000, v50
	v_mul_f32_e32 v59, v13, v56
	v_mul_f32_e32 v58, v12, v58
	v_fmac_f32_e32 v59, v11, v57
	v_add_f32_e32 v59, v58, v59
	v_cvt_pk_bf16_f32 v62, v55, v59
	v_lshlrev_b32_e32 v52, 16, v43
	v_lshlrev_b32_e32 v53, 16, v47
	v_lshlrev_b32_e32 v54, 16, v51
	v_mul_f32_e32 v55, v13, v52
	v_mul_f32_e32 v54, v12, v54
	v_fmac_f32_e32 v55, v11, v53
	v_add_f32_e32 v55, v54, v55
	v_and_b32_e32 v56, 0xffff0000, v43
	v_and_b32_e32 v57, 0xffff0000, v47
	v_and_b32_e32 v58, 0xffff0000, v51
	v_mul_f32_e32 v59, v13, v56
	v_mul_f32_e32 v58, v12, v58
	v_fmac_f32_e32 v59, v11, v57
	v_add_f32_e32 v59, v58, v59
	v_cvt_pk_bf16_f32 v63, v55, v59
	global_store_dwordx4 v[6:7], v[60:63], off offset:1024
	s_andn2_b64 exec, exec, s[38:39]
	s_cbranch_execnz .LBB0_355
